# GEMM_in/GEMM_out loops: first carried MFMA moved to right after the loop-back barrier (MFMA-first segment head), before the fragment reads
# speedup vs baseline: 1.0400x; 1.0010x over previous
; DI f32x16 mfma32(bf16x8 a, bf16x8 b, f32x16 c) { return __builtin_amdgcn_mfma_f32_32x32x16_bf16(a, b, c, 0, 0, 0); }
; #define RAW_BARRIER() do { asm volatile("s_waitcnt lgkmcnt(0)" ::: "memory"); __builtin_amdgcn_s_barrier(); } while (0)
; DI void gemm_tile(const Params& p, const GemmJob& j, int mt, int nt, char* smem) {
;     ...
;   for (int kt = 0; kt < nk; ++kt) {
;     if (kt + 1 < nk) asm volatile("s_waitcnt vmcnt(6)" ::: "memory"); else asm volatile("s_waitcnt vmcnt(0)" ::: "memory");
;     RAW_BARRIER();
;     if (kt + 2 < nk) glds(kt + 2, st2);
;     const char* sb = smem + st * GSTAGE;
; #pragma unroll
;     for (int ks = 0; ks < 2; ++ks) {
;       const int off = ks ? (o0 ^ 32) : o0;
;       bf16x8 wf[2], xf[4];
; #pragma unroll
;       for (int a = 0; a < 2; ++a) wf[a] = *(const bf16x8*)(sb + (64 * wn + 32 * a + r) * 64 + off);
; #pragma unroll
;       for (int b = 0; b < 4; ++b) xf[b] = *(const bf16x8*)(sb + 8192 + (128 * wt + 32 * b + r) * 64 + off);
; #pragma unroll
;       for (int a = 0; a < 2; ++a)
; #pragma unroll
;         for (int b = 0; b < 4; ++b) acc[a][b] = mfma32(wf[a], xf[b], acc[a][b]);
;     }
;     st = (st == 2) ? 0 : st + 1; st2 = (st2 == 2) ? 0 : st2 + 1;
;   }
.LBB0_103:
	s_add_i32 s37, s63, s33
	v_lshl_add_u64 v[232:233], v[232:233], 0, v[0:1]
	s_mov_b32 m0, s37
	v_lshl_add_u64 v[134:135], v[134:135], 0, 64
	global_load_lds_dwordx4 v[232:233], off
	v_lshl_add_u64 v[232:233], v[138:139], 0, s[8:9]
	v_lshl_add_u64 v[234:235], v[232:233], 0, s[92:93]
	s_add_i32 m0, s36, 0x2000
	s_add_i32 s36, s63, s55
	global_load_lds_dwordx4 v[234:235], off
	v_mfma_f32_32x32x16_bf16 v[66:81], v[236:239], v[244:247], v[66:81]
	v_lshl_add_u64 v[234:235], v[140:141], 0, s[8:9]
	s_add_i32 m0, s37, 0x2000
	v_lshl_add_u64 v[136:137], v[136:137], 0, 64
	global_load_lds_dwordx4 v[234:235], off
	v_mfma_f32_32x32x16_bf16 v[34:49], v[236:239], v[248:251], v[34:49]
	v_lshl_add_u64 v[234:235], v[232:233], 0, s[84:85]
	s_add_i32 m0, s36, 0x2000
	s_add_i32 s36, s63, s58
	global_load_lds_dwordx4 v[234:235], off
	v_mfma_f32_32x32x16_bf16 v[2:17], v[236:239], v[252:255], v[2:17]
	v_lshl_add_u64 v[232:233], v[232:233], 0, s[52:53]
	s_add_i32 m0, s36, 0x2000
	s_nop 0
	global_load_lds_dwordx4 v[232:233], off
	v_add_u32_e32 v234, s100, v150
	v_add_u32_e32 v235, v234, v149
	v_add_u32_e32 v234, v234, v148
	s_waitcnt lgkmcnt(0)
	v_mfma_f32_32x32x16_bf16 v[114:129], v[152:155], v[156:159], v[114:129]
	ds_read_b128 v[236:239], v143 offset:2048
	s_add_i32 s36, s11, 1
	s_cmp_lg_u32 s11, 2
	s_cselect_b32 s11, s36, 0
	s_add_i32 s36, s70, 1
	s_cmp_lg_u32 s70, 2
	s_cselect_b32 s70, s36, 0
	v_mfma_f32_32x32x16_bf16 v[82:97], v[152:155], v[160:163], v[82:97]
	ds_read_b128 v[240:243], v234 offset:8192
	s_add_u32 s8, s8, 0x200000
	s_addc_u32 s9, s9, 0
	s_add_i32 s62, s62, 1
	s_cmp_eq_u32 s8, 0x3c00000
	v_mfma_f32_32x32x16_bf16 v[50:65], v[152:155], v[180:183], v[50:65]
	ds_read_b128 v[244:247], v234 offset:10240
	v_mfma_f32_32x32x16_bf16 v[18:33], v[152:155], v[184:187], v[18:33]
	ds_read_b128 v[248:251], v234 offset:12288
	s_waitcnt lgkmcnt(3)
	v_mfma_f32_32x32x16_bf16 v[98:113], v[236:239], v[156:159], v[98:113]
	ds_read_b128 v[252:255], v234 offset:14336
	v_mfma_f32_32x32x16_bf16 v[66:81], v[236:239], v[160:163], v[66:81]
	ds_read_b128 v[152:155], v235
	v_mfma_f32_32x32x16_bf16 v[34:49], v[236:239], v[180:183], v[34:49]
	v_mfma_f32_32x32x16_bf16 v[2:17], v[236:239], v[184:187], v[2:17]
	ds_read_b128 v[236:239], v235 offset:2048
	s_waitcnt lgkmcnt(1)
	v_mfma_f32_32x32x16_bf16 v[114:129], v[152:155], v[240:243], v[114:129]
	v_mfma_f32_32x32x16_bf16 v[82:97], v[152:155], v[244:247], v[82:97]
	v_mfma_f32_32x32x16_bf16 v[50:65], v[152:155], v[248:251], v[50:65]
	v_mfma_f32_32x32x16_bf16 v[18:33], v[152:155], v[252:255], v[18:33]
	s_cbranch_scc1 .LBB0_108
.LBB0_104:
	s_waitcnt vmcnt(6)
	s_waitcnt lgkmcnt(0)
	s_add_i32 s37, s62, 2
	s_and_b64 vcc, exec, s[6:7]
	s_mul_i32 s38, s37, s3
	v_mov_b64_e32 v[232:233], v[134:135]
	s_mul_i32 s100, s11, 0x6000
	v_add_u32_e32 v142, s100, v147
	v_add_u32_e32 v143, v142, v149
	v_add_u32_e32 v142, v142, v148
	s_barrier
	v_mfma_f32_32x32x16_bf16 v[98:113], v[236:239], v[240:243], v[98:113]
	ds_read_b128 v[152:155], v143
	ds_read_b128 v[156:159], v142 offset:8192
	ds_read_b128 v[160:163], v142 offset:10240
	ds_read_b128 v[180:183], v142 offset:12288
	ds_read_b128 v[184:187], v142 offset:14336
	s_cbranch_vccnz .LBB0_106
	v_mov_b32_e32 v232, s2
	v_mad_u64_u32 v[232:233], s[40:41], s37, v232, v[130:131]
	v_add_u32_e32 v233, s38, v233
	v_lshlrev_b64 v[232:233], 6, v[232:233]
	v_lshl_add_u64 v[232:233], s[4:5], 0, v[232:233]

; DI f32x16 mfma32(bf16x8 a, bf16x8 b, f32x16 c) { return __builtin_amdgcn_mfma_f32_32x32x16_bf16(a, b, c, 0, 0, 0); }
; #define RAW_BARRIER() do { asm volatile("s_waitcnt lgkmcnt(0)" ::: "memory"); __builtin_amdgcn_s_barrier(); } while (0)
; DI void gemm_tile(const Params& p, const GemmJob& j, int mt, int nt, char* smem) {
;     ...
;   for (int kt = 0; kt < nk; ++kt) {
;     if (kt + 1 < nk) asm volatile("s_waitcnt vmcnt(6)" ::: "memory"); else asm volatile("s_waitcnt vmcnt(0)" ::: "memory");
;     RAW_BARRIER();
;     if (kt + 2 < nk) glds(kt + 2, st2);
;     const char* sb = smem + st * GSTAGE;
; #pragma unroll
;     for (int ks = 0; ks < 2; ++ks) {
;       const int off = ks ? (o0 ^ 32) : o0;
;       bf16x8 wf[2], xf[4];
; #pragma unroll
;       for (int a = 0; a < 2; ++a) wf[a] = *(const bf16x8*)(sb + (64 * wn + 32 * a + r) * 64 + off);
; #pragma unroll
;       for (int b = 0; b < 4; ++b) xf[b] = *(const bf16x8*)(sb + 8192 + (128 * wt + 32 * b + r) * 64 + off);
; #pragma unroll
;       for (int a = 0; a < 2; ++a)
; #pragma unroll
;         for (int b = 0; b < 4; ++b) acc[a][b] = mfma32(wf[a], xf[b], acc[a][b]);
;     }
;     st = (st == 2) ? 0 : st + 1; st2 = (st2 == 2) ? 0 : st2 + 1;
;   }
.LBB0_886:
	s_mul_i32 s10, s54, 0x6000
	s_add_i32 s36, s10, 0
	v_lshl_add_u64 v[142:143], v[132:133], 0, v[0:1]
	s_mov_b64 s[10:11], 0x20000
	s_add_i32 s37, s36, s55
	s_waitcnt vmcnt(6)
	v_lshl_add_u64 v[144:145], v[142:143], 0, s[10:11]
	s_mov_b32 m0, s37
	s_mov_b64 s[10:11], 0x21000
	s_add_i32 s38, s36, s58
	s_waitcnt lgkmcnt(0)
	s_mul_i32 s100, s6, 0x6000
	v_add_u32_e32 v141, s100, v137
	v_add_u32_e32 v146, v141, v140
	v_add_u32_e32 v141, v141, v139
	s_barrier
	v_mfma_f32_32x32x16_bf16 v[82:97], v[232:235], v[240:243], v[82:97]
	ds_read_b128 v[150:153], v141 offset:8192
	ds_read_b128 v[154:157], v141 offset:10240
	ds_read_b128 v[158:161], v141 offset:12288
	ds_read_b128 v[162:165], v141 offset:14336
	ds_read_b128 v[146:149], v146 offset:2048
	global_load_lds_dwordx4 v[144:145], off
	v_lshl_add_u64 v[142:143], v[142:143], 0, s[10:11]
	s_mov_b32 m0, s38
	s_mov_b64 s[10:11], 0x401000
	global_load_lds_dwordx4 v[142:143], off
	v_mfma_f32_32x32x16_bf16 v[50:65], v[232:235], v[244:247], v[50:65]
	v_lshl_add_u64 v[142:143], v[130:131], 0, v[0:1]
	v_lshl_add_u64 v[144:145], v[142:143], 0, s[92:93]
	s_add_i32 m0, s37, 0x2000
	v_lshl_add_u64 v[130:131], v[130:131], 0, s[88:89]
	global_load_lds_dwordx4 v[144:145], off
	v_mfma_f32_32x32x16_bf16 v[18:33], v[232:235], v[248:251], v[18:33]
	v_lshl_add_u64 v[144:145], v[142:143], 0, s[10:11]
	s_add_i32 m0, s38, 0x2000
	s_add_i32 s10, s36, s62
	global_load_lds_dwordx4 v[144:145], off
	v_mfma_f32_32x32x16_bf16 v[2:17], v[232:235], v[252:255], v[2:17]
	v_lshl_add_u64 v[144:145], v[142:143], 0, s[84:85]
	s_add_i32 m0, s10, 0x2000
	s_add_i32 s10, s36, s63
	global_load_lds_dwordx4 v[144:145], off
	v_mfma_f32_32x32x16_bf16 v[114:129], v[236:239], v[240:243], v[114:129]
	v_lshl_add_u64 v[142:143], v[142:143], 0, s[52:53]
	s_add_i32 m0, s10, 0x2000
	s_mul_i32 s10, s6, 0x6000
	global_load_lds_dwordx4 v[142:143], off
	v_mfma_f32_32x32x16_bf16 v[98:113], v[236:239], v[244:247], v[98:113]
	v_mfma_f32_32x32x16_bf16 v[66:81], v[236:239], v[248:251], v[66:81]
	v_mfma_f32_32x32x16_bf16 v[34:49], v[236:239], v[252:255], v[34:49]
	v_add_u32_e32 v142, s100, v137
	v_add_u32_e32 v142, v142, v140
	ds_read_b128 v[142:145], v142
	v_add_u32_e32 v252, s100, v138
	v_add_u32_e32 v236, v252, v140
	v_add_u32_e32 v252, v252, v139
	s_waitcnt lgkmcnt(1)
	v_mfma_f32_32x32x16_bf16 v[114:129], v[146:149], v[150:153], v[114:129]
	ds_read_b128 v[232:235], v236
	s_add_i32 s10, s6, 1
	s_cmp_lg_u32 s6, 2
	s_cselect_b32 s6, s10, 0
	s_add_i32 s10, s54, 1
	s_cmp_lg_u32 s54, 2
	s_cselect_b32 s54, s10, 0
	v_mfma_f32_32x32x16_bf16 v[98:113], v[146:149], v[154:157], v[98:113]
	ds_read_b128 v[236:239], v236 offset:2048
	s_add_i32 s7, s7, -1
	v_lshl_add_u64 v[132:133], v[132:133], 0, s[56:57]
	s_cmp_eq_u32 s7, 0
	v_mfma_f32_32x32x16_bf16 v[66:81], v[146:149], v[158:161], v[66:81]
	ds_read_b128 v[240:243], v252 offset:8192
	v_mfma_f32_32x32x16_bf16 v[34:49], v[146:149], v[162:165], v[34:49]
	ds_read_b128 v[244:247], v252 offset:10240
	s_waitcnt lgkmcnt(4)
	v_mfma_f32_32x32x16_bf16 v[82:97], v[142:145], v[150:153], v[82:97]
	ds_read_b128 v[248:251], v252 offset:12288
	v_mfma_f32_32x32x16_bf16 v[50:65], v[142:145], v[154:157], v[50:65]
	ds_read_b128 v[252:255], v252 offset:14336
	v_mfma_f32_32x32x16_bf16 v[18:33], v[142:145], v[158:161], v[18:33]
	v_mfma_f32_32x32x16_bf16 v[2:17], v[142:145], v[162:165], v[2:17]
	s_cbranch_scc0 .LBB0_886
	s_waitcnt lgkmcnt(0)
	v_mfma_f32_32x32x16_bf16 v[82:97], v[232:235], v[240:243], v[82:97]
	v_mfma_f32_32x32x16_bf16 v[50:65], v[232:235], v[244:247], v[50:65]
	v_mfma_f32_32x32x16_bf16 v[18:33], v[232:235], v[248:251], v[18:33]
	v_mfma_f32_32x32x16_bf16 v[2:17], v[232:235], v[252:255], v[2:17]
	v_mfma_f32_32x32x16_bf16 v[114:129], v[236:239], v[240:243], v[114:129]
	v_mfma_f32_32x32x16_bf16 v[98:113], v[236:239], v[244:247], v[98:113]
	v_mfma_f32_32x32x16_bf16 v[66:81], v[236:239], v[248:251], v[66:81]
	v_mfma_f32_32x32x16_bf16 v[34:49], v[236:239], v[252:255], v[34:49]
	s_mul_i32 s7, s6, 0x6000
	s_add_i32 s10, s7, 0
	v_add_u32_e32 v0, s10, v137
	s_waitcnt vmcnt(6)
	v_add_u32_e32 v141, v0, v140
	s_waitcnt lgkmcnt(0)
	s_barrier
	ds_read_b128 v[130:133], v141
	ds_read_b128 v[142:145], v141 offset:2048
	v_add_u32_e32 v0, v0, v139
	ds_read_b128 v[146:149], v0 offset:8192
	ds_read_b128 v[150:153], v0 offset:10240
	ds_read_b128 v[154:157], v0 offset:12288
	ds_read_b128 v[158:161], v0 offset:14336
	s_waitcnt lgkmcnt(0)
	v_mfma_f32_32x32x16_bf16 v[82:97], v[130:133], v[146:149], v[82:97]
	v_add_u32_e32 v0, s10, v138
	v_add_u32_e32 v141, v0, v140
	v_add_u32_e32 v0, v0, v139
	s_addk_i32 s7, 0x6000
	s_cmp_lg_u32 s6, 2
	s_cselect_b32 s6, s7, 0
	s_add_i32 s6, s6, 0
	v_mfma_f32_32x32x16_bf16 v[114:129], v[142:145], v[146:149], v[114:129]
	v_readlane_b32 s12, v229, 29
	v_readlane_b32 s22, v229, 39
	v_readlane_b32 s23, v229, 40
	v_readlane_b32 s18, v229, 35
	v_readlane_b32 s19, v229, 36
	s_mov_b32 s58, 0
	v_readlane_b32 s13, v229, 30
	v_mfma_f32_32x32x16_bf16 v[50:65], v[130:133], v[150:153], v[50:65]
	v_readlane_b32 s14, v229, 31
	v_readlane_b32 s15, v229, 32
	v_readlane_b32 s16, v229, 33
	v_readlane_b32 s17, v229, 34
	v_readlane_b32 s20, v229, 37
	v_readlane_b32 s21, v229, 38
	v_readlane_b32 s24, v229, 41
	v_mfma_f32_32x32x16_bf16 v[18:33], v[130:133], v[154:157], v[18:33]
	v_readlane_b32 s25, v229, 42
	v_readlane_b32 s26, v229, 43
	v_readlane_b32 s27, v229, 44
	v_mfma_f32_32x32x16_bf16 v[2:17], v[130:133], v[158:161], v[2:17]
	v_mfma_f32_32x32x16_bf16 v[98:113], v[142:145], v[150:153], v[98:113]
	v_mfma_f32_32x32x16_bf16 v[66:81], v[142:145], v[154:157], v[66:81]
	v_mfma_f32_32x32x16_bf16 v[34:49], v[142:145], v[158:161], v[34:49]
	ds_read_b128 v[130:133], v141
	ds_read_b128 v[142:145], v141 offset:2048
	ds_read_b128 v[146:149], v0 offset:8192
	ds_read_b128 v[150:153], v0 offset:10240
	ds_read_b128 v[154:157], v0 offset:12288
	ds_read_b128 v[158:161], v0 offset:14336
	v_add_u32_e32 v0, s6, v137
	s_waitcnt vmcnt(0)
	v_add_u32_e32 v137, v0, v140
	s_waitcnt lgkmcnt(0)
	s_barrier
; DI unsigned pack2(float a, float b) { f32x2 v = {a, b}; bf16x2_t r = __builtin_convertvector(v, bf16x2_t); return __builtin_bit_cast(unsigned, r); }
; DI void gemm_tile(const Params& p, const GemmJob& j, int mt, int nt, char* smem) {
;     ...
;   for (int kt = 0; kt < nk; ++kt) {
;     if (kt + 1 < nk) asm volatile("s_waitcnt vmcnt(6)" ::: "memory"); else asm volatile("s_waitcnt vmcnt(0)" ::: "memory");
;     RAW_BARRIER();
;     if (kt + 2 < nk) glds(kt + 2, st2);
;     const char* sb = smem + st * GSTAGE;
; #pragma unroll
;     for (int ks = 0; ks < 2; ++ks) {
;       const int off = ks ? (o0 ^ 32) : o0;
;       bf16x8 wf[2], xf[4];
; #pragma unroll
;       for (int a = 0; a < 2; ++a) wf[a] = *(const bf16x8*)(sb + (64 * wn + 32 * a + r) * 64 + off);
; #pragma unroll
;       for (int b = 0; b < 4; ++b) xf[b] = *(const bf16x8*)(sb + 8192 + (128 * wt + 32 * b + r) * 64 + off);
; #pragma unroll
;       for (int a = 0; a < 2; ++a)
; #pragma unroll
;         for (int b = 0; b < 4; ++b) acc[a][b] = mfma32(wf[a], xf[b], acc[a][b]);
;     }
;     st = (st == 2) ? 0 : st + 1; st2 = (st2 == 2) ? 0 : st2 + 1;
;   }
;     ...
;     bf16_t* Cs = (bf16_t*)smem;
; #pragma unroll
;     for (int ni = 0; ni < 4; ++ni)
; #pragma unroll
;       for (int mi = 0; mi < 2; ++mi)
; #pragma unroll
;         for (int g = 0; g < 4; ++g)
;           *(u32x2*)(Cs + (128 * wt + 32 * ni + r) * 136 + 64 * wn + 32 * mi + 8 * g + 4 * h) =
;               (u32x2){pack2(acc[mi][ni][4 * g], acc[mi][ni][4 * g + 1]), pack2(acc[mi][ni][4 * g + 2], acc[mi][ni][4 * g + 3])};
;     __syncthreads();
; #pragma unroll 4
;     for (int q = 0; q < 16; ++q) {
;       const int idx = tid + 256 * q, row = idx >> 4, col = (idx & 15) * 8;
;       const u32x4 av = *(const u32x4*)(Cs + row * 136 + col);
;       bf16_t* xq = j.xbp + blk(t0 + row, n0 + col, NTOK);
;       float rv[8];
;       if (j.res) {
;         const f32x4 r0 = *(const f32x4*)(j.res + (size_t)(t0 + row) * 1024 + n0 + col), r1 = *(const f32x4*)(j.res + (size_t)(t0 + row) * 1024 + n0 + col + 4);
;         rv[0] = r0[0]; rv[1] = r0[1]; rv[2] = r0[2]; rv[3] = r0[3]; rv[4] = r1[0]; rv[5] = r1[1]; rv[6] = r1[2]; rv[7] = r1[3];
;       } else {
;         const u32x4 rb = *(const u32x4*)xq;
; #pragma unroll
;         for (int e = 0; e < 4; ++e) { rv[2 * e] = bflo(rb[e]); rv[2 * e + 1] = bfhi(rb[e]); }
;       }
;       float o[8]; float ss = 0.f;
; #pragma unroll
	s_waitcnt lgkmcnt(0)
	v_mfma_f32_32x32x16_bf16 v[82:97], v[130:133], v[146:149], v[82:97]
	v_add_u32_e32 v0, v0, v139
	v_mfma_f32_32x32x16_bf16 v[114:129], v[142:145], v[146:149], v[114:129]
	v_mfma_f32_32x32x16_bf16 v[50:65], v[130:133], v[150:153], v[50:65]
	v_mfma_f32_32x32x16_bf16 v[18:33], v[130:133], v[154:157], v[18:33]
	v_mfma_f32_32x32x16_bf16 v[2:17], v[130:133], v[158:161], v[2:17]
	v_mfma_f32_32x32x16_bf16 v[98:113], v[142:145], v[150:153], v[98:113]
	v_mfma_f32_32x32x16_bf16 v[66:81], v[142:145], v[154:157], v[66:81]
	v_mfma_f32_32x32x16_bf16 v[34:49], v[142:145], v[158:161], v[34:49]
	ds_read_b128 v[130:133], v137
	ds_read_b128 v[142:145], v137 offset:2048
	ds_read_b128 v[146:149], v0 offset:8192
	ds_read_b128 v[150:153], v0 offset:10240
	ds_read_b128 v[154:157], v0 offset:12288
	ds_read_b128 v[158:161], v0 offset:14336
	v_add_u32_e32 v0, s6, v138
	v_add_u32_e32 v137, v0, v140
	v_add_u32_e32 v0, v0, v139
	s_and_b32 s6, s31, 0xfffff80
	s_waitcnt lgkmcnt(0)
	v_mfma_f32_32x32x16_bf16 v[82:97], v[130:133], v[146:149], v[82:97]
	v_mfma_f32_32x32x16_bf16 v[114:129], v[142:145], v[146:149], v[114:129]
	v_mfma_f32_32x32x16_bf16 v[50:65], v[130:133], v[150:153], v[50:65]
	v_mfma_f32_32x32x16_bf16 v[18:33], v[130:133], v[154:157], v[18:33]
	v_mfma_f32_32x32x16_bf16 v[2:17], v[130:133], v[158:161], v[2:17]
	v_mfma_f32_32x32x16_bf16 v[98:113], v[142:145], v[150:153], v[98:113]
	v_mfma_f32_32x32x16_bf16 v[66:81], v[142:145], v[154:157], v[66:81]
	v_mfma_f32_32x32x16_bf16 v[34:49], v[142:145], v[158:161], v[34:49]
	ds_read_b128 v[130:133], v137
	ds_read_b128 v[140:143], v137 offset:2048
	ds_read_b128 v[144:147], v0 offset:8192
	ds_read_b128 v[148:151], v0 offset:10240
	ds_read_b128 v[152:155], v0 offset:12288
	ds_read_b128 v[156:159], v0 offset:14336
	v_or_b32_e32 v0, s6, v136
	s_lshl_b32 s6, s33, 7
	s_add_i32 s6, s6, 0
	v_mul_lo_u32 v0, v0, s0
	s_waitcnt vmcnt(0) lgkmcnt(0)
	v_mfma_f32_32x32x16_bf16 v[82:97], v[130:133], v[144:147], v[82:97]
	s_barrier
	v_mfma_f32_32x32x16_bf16 v[114:129], v[140:143], v[144:147], v[114:129]
	s_nop 9
	v_cvt_pk_bf16_f32 v82, v82, v83
	v_cvt_pk_bf16_f32 v83, v84, v85
	v_cvt_pk_bf16_f32 v84, v86, v87
	v_cvt_pk_bf16_f32 v85, v88, v89
	v_mfma_f32_32x32x16_bf16 v[50:65], v[130:133], v[148:151], v[50:65]
	v_mfma_f32_32x32x16_bf16 v[18:33], v[130:133], v[152:155], v[18:33]
	s_nop 10
	v_cvt_pk_bf16_f32 v50, v50, v51
	v_cvt_pk_bf16_f32 v51, v52, v53
	v_cvt_pk_bf16_f32 v52, v54, v55
	v_cvt_pk_bf16_f32 v53, v56, v57
	v_mfma_f32_32x32x16_bf16 v[2:17], v[130:133], v[156:159], v[2:17]
	v_lshlrev_b32_e32 v130, 3, v135
	v_add3_u32 v0, s6, v130, v0
	ds_write2_b64 v0, v[82:83], v[84:85] offset1:2
	v_cvt_pk_bf16_f32 v82, v90, v91
	v_cvt_pk_bf16_f32 v83, v92, v93
	v_cvt_pk_bf16_f32 v84, v94, v95
	v_cvt_pk_bf16_f32 v85, v96, v97
	v_mfma_f32_32x32x16_bf16 v[34:49], v[140:143], v[156:159], v[34:49]
	ds_write2_b64 v0, v[82:83], v[84:85] offset0:4 offset1:6
	v_cvt_pk_bf16_f32 v82, v114, v115
	v_cvt_pk_bf16_f32 v83, v116, v117
	v_cvt_pk_bf16_f32 v84, v118, v119
	v_cvt_pk_bf16_f32 v85, v120, v121
	ds_write2_b64 v0, v[82:83], v[84:85] offset0:8 offset1:10
	v_cvt_pk_bf16_f32 v82, v122, v123
	v_cvt_pk_bf16_f32 v83, v124, v125
	v_cvt_pk_bf16_f32 v84, v126, v127
	v_cvt_pk_bf16_f32 v85, v128, v129
	ds_write2_b64 v0, v[82:83], v[84:85] offset0:12 offset1:14
	v_add_u32_e32 v54, 0x2000, v0
	v_cvt_pk_bf16_f32 v18, v18, v19
	v_cvt_pk_bf16_f32 v19, v20, v21
	v_cvt_pk_bf16_f32 v20, v22, v23
	v_add_u32_e32 v22, 0x4000, v0
	v_cvt_pk_bf16_f32 v2, v2, v3
	v_cvt_pk_bf16_f32 v3, v4, v5
	v_cvt_pk_bf16_f32 v4, v6, v7
	v_cvt_pk_bf16_f32 v5, v8, v9
	v_add_u32_e32 v0, 0x6000, v0
	ds_write2_b64 v0, v[2:3], v[4:5] offset0:192 offset1:194
	v_cvt_pk_bf16_f32 v2, v10, v11
	v_cvt_pk_bf16_f32 v3, v12, v13
	v_cvt_pk_bf16_f32 v4, v14, v15
	v_cvt_pk_bf16_f32 v5, v16, v17
	ds_write2_b64 v0, v[2:3], v[4:5] offset0:196 offset1:198
	v_cvt_pk_bf16_f32 v2, v34, v35
	v_cvt_pk_bf16_f32 v3, v36, v37
	v_cvt_pk_bf16_f32 v4, v38, v39
	v_cvt_pk_bf16_f32 v5, v40, v41
	ds_write2_b64 v0, v[2:3], v[4:5] offset0:200 offset1:202
	v_cvt_pk_bf16_f32 v2, v42, v43
	v_cvt_pk_bf16_f32 v3, v44, v45
	v_cvt_pk_bf16_f32 v4, v46, v47
	v_cvt_pk_bf16_f32 v5, v48, v49
	ds_write2_b64 v0, v[2:3], v[4:5] offset0:204 offset1:206
	v_and_b32_e32 v2, 64, v202
	v_and_b32_e32 v3, 15, v134
	v_add_u32_e32 v2, 64, v2
	v_cmp_eq_u32_e32 vcc, 0, v3
	v_xor_b32_e32 v3, 1, v202
	v_cmp_lt_i32_e64 s[6:7], v3, v2
	v_mfma_f32_32x32x16_bf16 v[66:81], v[140:143], v[152:155], v[66:81]
	v_cvt_pk_bf16_f32 v21, v24, v25
	v_cndmask_b32_e64 v3, v202, v3, s[6:7]
	v_lshlrev_b32_e32 v15, 2, v3
	v_xor_b32_e32 v3, 2, v202
	v_cmp_lt_i32_e64 s[6:7], v3, v2
	v_lshlrev_b32_e32 v0, 3, v134
	v_and_b32_e32 v4, 0x78, v0
	v_cndmask_b32_e64 v3, v202, v3, s[6:7]
	v_lshlrev_b32_e32 v24, 2, v3
	v_xor_b32_e32 v3, 4, v202
	v_cmp_lt_i32_e64 s[6:7], v3, v2
	v_mfma_f32_32x32x16_bf16 v[98:113], v[140:143], v[148:151], v[98:113]
	v_or_b32_sdwa v0, s30, v4 dst_sel:WORD_1 dst_unused:UNUSED_PAD src0_sel:DWORD src1_sel:DWORD
	v_cndmask_b32_e64 v3, v202, v3, s[6:7]
	v_lshlrev_b32_e32 v25, 2, v3
	v_xor_b32_e32 v3, 8, v202
	v_cmp_lt_i32_e64 s[6:7], v3, v2
	v_and_b32_e32 v0, 0x3e00000, v0
	ds_write2_b64 v22, v[18:19], v[20:21] offset0:128 offset1:130
	v_cndmask_b32_e64 v2, v202, v3, s[6:7]
	v_cvt_pk_bf16_f32 v18, v26, v27
	v_cvt_pk_bf16_f32 v19, v28, v29
	v_cvt_pk_bf16_f32 v20, v30, v31
	v_cvt_pk_bf16_f32 v21, v32, v33
	v_lshlrev_b32_e32 v26, 2, v2
	v_lshl_add_u64 v[2:3], s[22:23], 0, v[0:1]
	v_lshlrev_b32_e32 v0, 4, v134
	s_lshl_b32 s6, s30, 2
	ds_write2_b64 v22, v[18:19], v[20:21] offset0:132 offset1:134
	v_cvt_pk_bf16_f32 v18, v66, v67
	v_cvt_pk_bf16_f32 v19, v68, v69
	v_cvt_pk_bf16_f32 v20, v70, v71
	v_cvt_pk_bf16_f32 v21, v72, v73
	v_and_b32_e32 v0, 48, v0
	s_add_u32 s6, s4, s6
	ds_write2_b64 v22, v[18:19], v[20:21] offset0:136 offset1:138
	v_cvt_pk_bf16_f32 v18, v74, v75
	v_cvt_pk_bf16_f32 v19, v76, v77
	v_cvt_pk_bf16_f32 v20, v78, v79
	v_cvt_pk_bf16_f32 v21, v80, v81
	v_lshl_add_u64 v[16:17], v[2:3], 0, v[0:1]
	s_addc_u32 s7, s5, 0
	v_lshlrev_b32_e32 v0, 2, v4
	ds_write2_b64 v54, v[50:51], v[52:53] offset0:64 offset1:66
	v_cvt_pk_bf16_f32 v50, v58, v59
	v_cvt_pk_bf16_f32 v51, v60, v61
	v_cvt_pk_bf16_f32 v52, v62, v63
	v_cvt_pk_bf16_f32 v53, v64, v65
	ds_write2_b64 v22, v[18:19], v[20:21] offset0:140 offset1:142
	v_lshl_add_u64 v[18:19], s[6:7], 0, v[0:1]
	s_and_b64 s[10:11], vcc, s[72:73]
	s_lshl_b32 s6, s29, 2
	ds_write2_b64 v54, v[50:51], v[52:53] offset0:68 offset1:70
	v_cvt_pk_bf16_f32 v50, v98, v99
	v_cvt_pk_bf16_f32 v51, v100, v101
	v_cvt_pk_bf16_f32 v52, v102, v103
	v_cvt_pk_bf16_f32 v53, v104, v105
	s_add_u32 s54, s18, s6
	ds_write2_b64 v54, v[50:51], v[52:53] offset0:72 offset1:74
	v_cvt_pk_bf16_f32 v50, v106, v107
	v_cvt_pk_bf16_f32 v51, v108, v109
	v_cvt_pk_bf16_f32 v52, v110, v111
	v_cvt_pk_bf16_f32 v53, v112, v113
	v_lshl_add_u32 v14, v4, 1, 0
	s_addc_u32 s55, s19, 0
	ds_write2_b64 v54, v[50:51], v[52:53] offset0:76 offset1:78
	s_waitcnt lgkmcnt(0)
	s_barrier
